# baseline (speedup 1.0000x reference)
.LBB0_1411:
	s_or_b64 exec, exec, s[0:1]
	s_cmpk_gt_i32 s79, 0x57
	s_cselect_b64 s[2:3], -1, 0
	s_xor_b64 s[4:5], s[8:9], -1
	s_or_b64 s[2:3], s[2:3], s[4:5]
	s_mov_b64 s[0:1], -1
	s_and_b64 vcc, exec, s[2:3]
	s_barrier
	s_cbranch_vccz .LBB0_1415
	s_movk_i32 s33, 0xcc0
	s_andn2_b64 vcc, exec, s[8:9]
	s_mov_b32 s52, s77
	s_cbranch_vccnz .LBB0_1414
	s_sleep 127
	s_sleep 127
	s_sleep 127
	s_sleep 127
	s_sleep 127
	s_sleep 127
	s_sleep 127
	s_sleep 127
	s_sleep 127
	s_sleep 127
	s_sleep 127
	s_sleep 127
	s_sleep 127
	s_sleep 127
	s_sleep 127
	s_sleep 127
	s_sleep 127
	s_sleep 127
	s_add_i32 s36, s79, 0xffffffa8
	s_movk_i32 s52, 0xa8
	s_movk_i32 s33, 0x9a8
